# FoX P*V: V^T fragment reads issued one or two MFMAs ahead of use through the idle quad v[236:239] (same operands and accumulation order)
# baseline (speedup 1.0000x reference)
; #define LAS __attribute__((address_space(3)))
; DI unsigned pk2(float lo, float hi) { f32x2_t v = {lo, hi}; bf16x2_t b = __builtin_convertvector(v, bf16x2_t); return __builtin_bit_cast(unsigned, b); }
; DI float max2f(float a, float b) { float r; asm("v_max_f32_e32 %0, %1, %2" : "=v"(r) : "v"(a), "v"(b)); return r; }
; #define MFMA32(a, b, c) __builtin_amdgcn_mfma_f32_32x32x16_bf16((a), (b), (c), 0, 0, 0)
; template <int MODE> DI void attn_unit(int b, int qb, const bf16* Qb, int qpitch, const bf16* Kb, int kpitch, const bf16* VT, bf16* O, float* ssq, ...
;     ...
;             const float mn = max2f(m, rm), corr = __builtin_amdgcn_exp2f(m - mn);
;             m = mn;
;             float rs = 0.f;
; #pragma unroll
;             for (int r = 0; r < 16; ++r) { p0[r] = __builtin_amdgcn_exp2f(p0[r] - mn); p1[r] = __builtin_amdgcn_exp2f(p1[r] - mn); rs += p0[r] + p1[r]; }
;             lsum = lsum * corr + rs;
;             if (__any(corr != 1.0f)) {
; #pragma unroll
;                 for (int r = 0; r < 16; ++r) { o0[r] *= corr; o1[r] *= corr; }
;             }
;             seen = true;
;             const LAS unsigned char* vb = lds + VOFF + buf * VSZ + r32 * 136 + 8 * hi;
; #pragma unroll
;             for (int s4 = 0; s4 < 4; ++s4) {
;                 v4u pw;
;                 if (s4 == 0) { pw.x = pk2(p0[0], p0[1]); pw.y = pk2(p0[2], p0[3]); pw.z = pk2(p0[4], p0[5]); pw.w = pk2(p0[6], p0[7]); }
;                 if (s4 == 1) { pw.x = pk2(p0[8], p0[9]); pw.y = pk2(p0[10], p0[11]); pw.z = pk2(p0[12], p0[13]); pw.w = pk2(p0[14], p0[15]); }
;                 if (s4 == 2) { pw.x = pk2(p1[0], p1[1]); pw.y = pk2(p1[2], p1[3]); pw.z = pk2(p1[4], p1[5]); pw.w = pk2(p1[6], p1[7]); }
;                 if (s4 == 3) { pw.x = pk2(p1[8], p1[9]); pw.y = pk2(p1[10], p1[11]); pw.z = pk2(p1[12], p1[13]); pw.w = pk2(p1[14], p1[15]); }
;                 const v8s pf = __builtin_bit_cast(v8s, pw);
;                 const v2u a0 = *(const LAS v2u*)(vb + 32 * s4), a1 = *(const LAS v2u*)(vb + 32 * s4 + 16);
;                 const v2u c0 = *(const LAS v2u*)(vb + 32 * 136 + 32 * s4), c1 = *(const LAS v2u*)(vb + 32 * 136 + 32 * s4 + 16);
;                 const v4u va = {a0.x, a0.y, a1.x, a1.y}, vc2 = {c0.x, c0.y, c1.x, c1.y};
;                 o0 = MFMA32(__builtin_bit_cast(v8s, va), pf, o0);
;                 o1 = MFMA32(__builtin_bit_cast(v8s, vc2), pf, o1);
;             }
.LBB0_513:
	v_sub_f32_e32 v46, v188, v43
	v_sub_f32_e32 v32, v32, v43
	v_exp_f32_e32 v46, v46
	v_exp_f32_e32 v32, v32
	v_sub_f32_e32 v60, v189, v43
	v_sub_f32_e32 v33, v33, v43
	v_exp_f32_e32 v60, v60
	v_exp_f32_e32 v33, v33
	v_add_f32_e32 v47, v32, v46
	v_add_f32_e32 v47, 0, v47
	v_sub_f32_e32 v34, v34, v43
	v_add_f32_e32 v61, v33, v60
	v_add_f32_e32 v47, v61, v47
	v_sub_f32_e32 v61, v186, v43
	v_exp_f32_e32 v61, v61
	v_exp_f32_e32 v34, v34
	v_sub_f32_e32 v35, v35, v43
	v_exp_f32_e32 v35, v35
	v_sub_f32_e32 v58, v58, v43
	v_add_f32_e32 v62, v34, v61
	v_add_f32_e32 v47, v62, v47
	v_sub_f32_e32 v62, v187, v43
	v_exp_f32_e32 v62, v62
	v_exp_f32_e32 v58, v58
	v_sub_f32_e32 v59, v59, v43
	v_exp_f32_e32 v59, v59
	v_add_f32_e32 v63, v35, v62
	v_add_f32_e32 v47, v63, v47
	v_sub_f32_e32 v63, v184, v43
	v_exp_f32_e32 v63, v63
	v_sub_f32_e32 v38, v38, v43
	v_exp_f32_e32 v173, v38
	v_sub_f32_e32 v39, v39, v43
	v_add_f32_e32 v169, v58, v63
	v_add_f32_e32 v47, v169, v47
	v_sub_f32_e32 v169, v185, v43
	v_exp_f32_e32 v169, v169
	v_exp_f32_e32 v39, v39
	v_sub_f32_e32 v54, v54, v43
	v_sub_f32_e32 v56, v56, v43
	v_add_f32_e32 v172, v59, v169
	v_add_f32_e32 v47, v172, v47
	v_sub_f32_e32 v172, v182, v43
	v_exp_f32_e32 v172, v172
	v_exp_f32_e32 v54, v54
	v_exp_f32_e32 v56, v56
	v_sub_f32_e32 v55, v55, v43
	v_add_f32_e32 v38, v173, v172
	v_add_f32_e32 v38, v38, v47
	v_sub_f32_e32 v47, v183, v43
	v_exp_f32_e32 v47, v47
	v_sub_f32_e32 v57, v57, v43
	v_exp_f32_e32 v55, v55
	v_exp_f32_e32 v57, v57
	v_add_f32_e32 v182, v39, v47
	v_add_f32_e32 v38, v182, v38
	v_add_f32_e32 v182, v56, v54
	v_add_f32_e32 v38, v182, v38
	v_add_f32_e32 v182, v57, v55
	v_sub_f32_e32 v48, v48, v43
	v_sub_f32_e32 v40, v40, v43
	v_add_f32_e32 v38, v182, v38
	v_exp_f32_e32 v182, v48
	v_exp_f32_e32 v183, v40
	v_sub_f32_e32 v36, v36, v43
	v_exp_f32_e32 v187, v36
	v_sub_f32_e32 v37, v37, v43
	v_add_f32_e32 v40, v183, v182
	v_add_f32_e32 v38, v40, v38
	v_sub_f32_e32 v40, v49, v43
	v_exp_f32_e32 v49, v40
	v_sub_f32_e32 v40, v41, v43
	v_exp_f32_e32 v41, v40
	v_exp_f32_e32 v188, v37
	s_mul_i32 s24, s72, 0x2200
	v_cvt_pk_bf16_f32 v48, v54, v55
	v_add_f32_e32 v40, v41, v49
	v_add_f32_e32 v38, v40, v38
	v_sub_f32_e32 v40, v52, v43
	v_exp_f32_e32 v52, v40
	v_sub_f32_e32 v40, v44, v43
	v_exp_f32_e32 v184, v40
	v_cvt_pk_bf16_f32 v44, v46, v60
	v_cvt_pk_bf16_f32 v46, v63, v169
	v_cvt_pk_bf16_f32 v47, v172, v47
	v_add_f32_e32 v40, v184, v52
	v_add_f32_e32 v38, v40, v38
	v_sub_f32_e32 v40, v53, v43
	v_exp_f32_e32 v53, v40
	v_sub_f32_e32 v40, v45, v43
	v_exp_f32_e32 v185, v40
	v_cvt_pk_bf16_f32 v45, v61, v62
	v_cvt_pk_bf16_f32 v49, v182, v49
	v_cvt_pk_bf16_f32 v39, v173, v39
	v_add_f32_e32 v40, v185, v53
	v_add_f32_e32 v38, v40, v38
	v_sub_f32_e32 v40, v50, v43
	v_exp_f32_e32 v186, v40
	v_cvt_pk_bf16_f32 v50, v52, v53
	v_mov_b32_e32 v169, v43
	v_add_f32_e32 v36, v187, v186
	v_add_f32_e32 v36, v36, v38
	v_sub_f32_e32 v38, v51, v43
	v_exp_f32_e32 v38, v38
	s_nop 0
	v_add_f32_e32 v37, v188, v38
	v_add_f32_e32 v40, v37, v36
	v_fmac_f32_e32 v40, v157, v42
	v_add_u32_e32 v42, s24, v200
	v_cvt_pk_bf16_f32 v36, v32, v33
	v_cvt_pk_bf16_f32 v33, v183, v41
	v_add_u32_e32 v41, 0x4800, v42
	v_add_u32_e32 v42, 0x5800, v42
	v_cvt_pk_bf16_f32 v51, v186, v38
	v_cvt_pk_bf16_f32 v38, v58, v59
	v_cvt_pk_bf16_f32 v32, v56, v57
	ds_read2_b64 v[52:55], v41 offset1:2
	ds_read2_b64 v[56:59], v41 offset0:4 offset1:6
	ds_read2_b64 v[60:63], v42 offset0:32 offset1:34
	ds_read2_b64 v[236:239], v42 offset0:36 offset1:38
	s_waitcnt lgkmcnt(3)
	v_mfma_f32_32x32x16_bf16 v[16:31], v[52:55], v[44:47], v[16:31]
	v_cvt_pk_bf16_f32 v37, v34, v35
	v_cvt_pk_bf16_f32 v34, v184, v185
	v_cvt_pk_bf16_f32 v35, v187, v188
	s_mov_b64 s[24:25], -1
	v_mov_b32_e32 v157, v40
	s_waitcnt lgkmcnt(1)
	v_mfma_f32_32x32x16_bf16 v[0:15], v[60:63], v[44:47], v[0:15]
	ds_read2_b64 v[44:47], v41 offset0:8 offset1:10
	v_mfma_f32_32x32x16_bf16 v[16:31], v[56:59], v[48:51], v[16:31]
	s_waitcnt lgkmcnt(1)
	v_mfma_f32_32x32x16_bf16 v[0:15], v[236:239], v[48:51], v[0:15]
	ds_read2_b64 v[48:51], v42 offset0:40 offset1:42
	ds_read2_b64 v[236:239], v41 offset0:12 offset1:14
	s_waitcnt lgkmcnt(2)
	v_mfma_f32_32x32x16_bf16 v[16:31], v[44:47], v[36:39], v[16:31]
	s_waitcnt lgkmcnt(1)
	v_mfma_f32_32x32x16_bf16 v[0:15], v[48:51], v[36:39], v[0:15]
	ds_read2_b64 v[44:47], v42 offset0:44 offset1:46
	s_waitcnt lgkmcnt(1)
	v_mfma_f32_32x32x16_bf16 v[16:31], v[236:239], v[32:35], v[16:31]
	s_waitcnt lgkmcnt(0)
	v_mfma_f32_32x32x16_bf16 v[0:15], v[44:47], v[32:35], v[0:15]
	s_andn2_b64 vcc, exec, s[22:23]
	s_cbranch_vccnz .LBB0_517
